# static priority raise (s_setprio 3/0) around the single-wave RG-LRU scan, the serial chain every other wave of the workgroup waits on
# baseline (speedup 1.0000x reference)
.Llru32_noba:
	v_mfma_f32_16x16x32_bf16 v[44:47], v[56:59], v[60:63], v[44:47]
	ds_read_b128 v[68:71], v209
	ds_read_b128 v[60:63], v210
	ds_read_b128 v[56:59], v211
	ds_read_b64 v[164:165], v162
	s_waitcnt lgkmcnt(3)
	v_add_f32_e32 v64, v64, v68
	v_mul_f32_e32 v64, 0xbfb8aa3b, v64
	v_exp_f32_e32 v64, v64
	s_waitcnt lgkmcnt(2)
	v_add_f32_e32 v52, v52, v60
	v_mul_f32_e32 v52, 0xbfb8aa3b, v52
	v_exp_f32_e32 v60, v52
	v_add_f32_e32 v64, 1.0, v64
	v_div_scale_f32 v68, s[0:1], v64, v64, 1.0
	v_rcp_f32_e32 v180, v68
	v_add_f32_e32 v53, v53, v61
	v_mul_f32_e32 v53, 0xbfb8aa3b, v53
	v_exp_f32_e32 v61, v53
	v_fma_f32 v181, -v68, v180, 1.0
	v_fmac_f32_e32 v180, v181, v180
	v_div_scale_f32 v181, vcc, 1.0, v64, 1.0
	v_mul_f32_e32 v182, v181, v180
	v_fma_f32 v186, -v68, v182, v181
	v_fmac_f32_e32 v182, v186, v180
	v_fma_f32 v68, -v68, v182, v181
	v_div_fmas_f32 v68, v68, v180, v182
	v_div_fixup_f32 v64, v68, v64, 1.0
	v_mul_f32_e32 v52, 0xc1000000, v64
	s_waitcnt lgkmcnt(1)
	v_mul_f32_e32 v52, v56, v52
	v_mul_f32_e32 v52, 0x3fb8aa3b, v52
	v_exp_f32_e32 v52, v52
	v_add_f32_e32 v54, v54, v62
	v_mul_f32_e32 v54, 0xbfb8aa3b, v54
	v_exp_f32_e32 v62, v54
	v_fma_f32 v56, -v52, v52, 1.0
	v_max_f32_e32 v56, 0, v56
	v_cmp_gt_f32_e32 vcc, s10, v56
	v_mul_f32_e32 v64, 0x4f800000, v56
	v_add_f32_e32 v55, v55, v63
	v_cndmask_b32_e32 v56, v56, v64, vcc
	v_sqrt_f32_e32 v64, v56
	v_mul_f32_e32 v55, 0xbfb8aa3b, v55
	v_exp_f32_e32 v63, v55
	v_pk_add_f32 v[60:61], v[60:61], 1.0 op_sel_hi:[1,0]
	v_add_u32_e32 v68, -1, v64
	v_fma_f32 v180, -v68, v64, v56
	v_cmp_ge_f32_e64 s[0:1], 0, v180
	v_add_u32_e32 v180, 1, v64
	v_pk_add_f32 v[62:63], v[62:63], 1.0 op_sel_hi:[1,0]
	v_cndmask_b32_e64 v68, v64, v68, s[0:1]
	v_fma_f32 v64, -v180, v64, v56
	v_cmp_lt_f32_e64 s[0:1], 0, v64
	s_waitcnt lgkmcnt(0)
	v_lshlrev_b32_e32 v162, 16, v164
	v_and_b32_e32 v163, 0xffff0000, v164
	v_cndmask_b32_e64 v64, v68, v180, s[0:1]
	v_mul_f32_e32 v68, 0x37800000, v64
	v_cndmask_b32_e32 v64, v64, v68, vcc
	v_cmp_class_f32_e32 vcc, v56, v169
	v_lshlrev_b32_e32 v164, 16, v165
	v_and_b32_e32 v165, 0xffff0000, v165
	v_cndmask_b32_e32 v56, v64, v56, vcc
	v_add_f32_e32 v64, v65, v69
	v_mul_f32_e32 v64, 0xbfb8aa3b, v64
	v_exp_f32_e32 v64, v64
	s_nop 0
	v_add_f32_e32 v64, 1.0, v64
	v_div_scale_f32 v65, s[0:1], v64, v64, 1.0
	v_rcp_f32_e32 v68, v65
	s_nop 0
	v_fma_f32 v69, -v65, v68, 1.0
	v_fmac_f32_e32 v68, v69, v68
	v_div_scale_f32 v69, vcc, 1.0, v64, 1.0
	v_mul_f32_e32 v180, v69, v68
	v_fma_f32 v181, -v65, v180, v69
	v_fmac_f32_e32 v180, v181, v68
	v_fma_f32 v65, -v65, v180, v69
	v_div_fmas_f32 v65, v65, v68, v180
	v_div_fixup_f32 v64, v65, v64, 1.0
	v_mul_f32_e32 v53, 0xc1000000, v64
	v_mul_f32_e32 v53, v57, v53
	v_mul_f32_e32 v53, 0x3fb8aa3b, v53
	v_exp_f32_e32 v53, v53
	s_nop 0
	v_fma_f32 v57, -v53, v53, 1.0
	v_max_f32_e32 v57, 0, v57
	v_cmp_gt_f32_e32 vcc, s10, v57
	v_mul_f32_e32 v64, 0x4f800000, v57
	s_nop 0
	v_cndmask_b32_e32 v57, v57, v64, vcc
	v_sqrt_f32_e32 v64, v57
	s_nop 0
	v_add_u32_e32 v65, -1, v64
	v_fma_f32 v68, -v65, v64, v57
	v_cmp_ge_f32_e64 s[0:1], 0, v68
	v_add_u32_e32 v68, 1, v64
	s_nop 0
	v_cndmask_b32_e64 v65, v64, v65, s[0:1]
	v_fma_f32 v64, -v68, v64, v57
	v_cmp_lt_f32_e64 s[0:1], 0, v64
	s_nop 1
	v_cndmask_b32_e64 v64, v65, v68, s[0:1]
	v_mul_f32_e32 v65, 0x37800000, v64
	v_cndmask_b32_e32 v64, v64, v65, vcc
	v_cmp_class_f32_e32 vcc, v57, v169
	s_nop 1
	v_cndmask_b32_e32 v57, v64, v57, vcc
	v_add_f32_e32 v64, v66, v70
	v_mul_f32_e32 v64, 0xbfb8aa3b, v64
	v_exp_f32_e32 v64, v64
	s_nop 0
	v_add_f32_e32 v64, 1.0, v64
	v_div_scale_f32 v65, s[0:1], v64, v64, 1.0
	v_rcp_f32_e32 v66, v65
	s_nop 0
	v_fma_f32 v68, -v65, v66, 1.0
	v_fmac_f32_e32 v66, v68, v66
	v_div_scale_f32 v68, vcc, 1.0, v64, 1.0
	v_mul_f32_e32 v69, v68, v66
	v_fma_f32 v70, -v65, v69, v68
	v_fmac_f32_e32 v69, v70, v66
	v_fma_f32 v65, -v65, v69, v68
	v_div_fmas_f32 v65, v65, v66, v69
	v_div_fixup_f32 v64, v65, v64, 1.0
	v_mul_f32_e32 v54, 0xc1000000, v64
	v_mul_f32_e32 v54, v58, v54
	v_mul_f32_e32 v54, 0x3fb8aa3b, v54
	v_exp_f32_e32 v54, v54
	s_nop 0
	v_fma_f32 v58, -v54, v54, 1.0
	v_max_f32_e32 v58, 0, v58
	v_cmp_gt_f32_e32 vcc, s10, v58
	v_mul_f32_e32 v64, 0x4f800000, v58
	s_nop 0
	v_cndmask_b32_e32 v58, v58, v64, vcc
	v_sqrt_f32_e32 v64, v58
	s_nop 0
	v_add_u32_e32 v65, -1, v64
	v_fma_f32 v66, -v65, v64, v58
	v_cmp_ge_f32_e64 s[0:1], 0, v66
	v_add_u32_e32 v66, 1, v64
	s_nop 0
	v_cndmask_b32_e64 v65, v64, v65, s[0:1]
	v_fma_f32 v64, -v66, v64, v58
	v_cmp_lt_f32_e64 s[0:1], 0, v64
	s_nop 1
	v_cndmask_b32_e64 v64, v65, v66, s[0:1]
	v_mul_f32_e32 v65, 0x37800000, v64
	v_cndmask_b32_e32 v64, v64, v65, vcc
	v_cmp_class_f32_e32 vcc, v58, v169
	s_nop 1
	v_cndmask_b32_e32 v58, v64, v58, vcc
	v_add_f32_e32 v64, v67, v71
	v_mul_f32_e32 v64, 0xbfb8aa3b, v64
	v_exp_f32_e32 v64, v64
	s_nop 0
	v_add_f32_e32 v64, 1.0, v64
	v_div_scale_f32 v65, s[0:1], v64, v64, 1.0
	v_rcp_f32_e32 v66, v65
	s_nop 0
	v_fma_f32 v67, -v65, v66, 1.0
	v_fmac_f32_e32 v66, v67, v66
	v_div_scale_f32 v67, vcc, 1.0, v64, 1.0
	v_mul_f32_e32 v68, v67, v66
	v_fma_f32 v69, -v65, v68, v67
	v_fmac_f32_e32 v68, v69, v66
	v_fma_f32 v65, -v65, v68, v67
	v_div_fmas_f32 v65, v65, v66, v68
	v_div_fixup_f32 v64, v65, v64, 1.0
	v_mul_f32_e32 v55, 0xc1000000, v64
	v_mul_f32_e32 v55, v59, v55
	v_mul_f32_e32 v55, 0x3fb8aa3b, v55
	v_exp_f32_e32 v55, v55
	s_nop 0
	v_fma_f32 v59, -v55, v55, 1.0
	v_max_f32_e32 v59, 0, v59
	v_cmp_gt_f32_e32 vcc, s10, v59
	v_mul_f32_e32 v64, 0x4f800000, v59
	s_nop 0
	v_cndmask_b32_e32 v59, v59, v64, vcc
	v_sqrt_f32_e32 v64, v59
	s_nop 0
	v_add_u32_e32 v65, -1, v64
	v_fma_f32 v66, -v65, v64, v59
	v_cmp_ge_f32_e64 s[0:1], 0, v66
	v_add_u32_e32 v66, 1, v64
	s_nop 0
	v_cndmask_b32_e64 v65, v64, v65, s[0:1]
	v_fma_f32 v64, -v66, v64, v59
	v_cmp_lt_f32_e64 s[0:1], 0, v64
	s_nop 1
	v_cndmask_b32_e64 v64, v65, v66, s[0:1]
	v_mul_f32_e32 v65, 0x37800000, v64
	v_cndmask_b32_e32 v64, v64, v65, vcc
	v_cmp_class_f32_e32 vcc, v59, v169
	s_nop 1
	v_cndmask_b32_e32 v59, v64, v59, vcc
	v_div_scale_f32 v64, s[0:1], v63, v63, 1.0
	v_rcp_f32_e32 v65, v64
	s_nop 0
	v_fma_f32 v66, -v64, v65, 1.0
	v_fmac_f32_e32 v65, v66, v65
	v_div_scale_f32 v66, vcc, 1.0, v63, 1.0
	v_mul_f32_e32 v67, v66, v65
	v_fma_f32 v68, -v64, v67, v66
	v_fmac_f32_e32 v67, v68, v65
	v_fma_f32 v64, -v64, v67, v66
	v_div_fmas_f32 v64, v64, v65, v67
	v_div_fixup_f32 v63, v64, v63, 1.0
	v_div_scale_f32 v64, s[0:1], v62, v62, 1.0
	v_rcp_f32_e32 v65, v64
	s_nop 0
	v_fma_f32 v66, -v64, v65, 1.0
	v_fmac_f32_e32 v65, v66, v65
	v_div_scale_f32 v66, vcc, 1.0, v62, 1.0
	v_mul_f32_e32 v67, v66, v65
	v_fma_f32 v68, -v64, v67, v66
	v_fmac_f32_e32 v67, v68, v65
	v_fma_f32 v64, -v64, v67, v66
	v_div_fmas_f32 v64, v64, v65, v67
	v_div_fixup_f32 v62, v64, v62, 1.0
	v_div_scale_f32 v64, s[0:1], v61, v61, 1.0
	v_rcp_f32_e32 v65, v64
	v_pk_mul_f32 v[58:59], v[62:63], v[58:59]
	v_fma_f32 v66, -v64, v65, 1.0
	v_fmac_f32_e32 v65, v66, v65
	v_div_scale_f32 v66, vcc, 1.0, v61, 1.0
	v_mul_f32_e32 v67, v66, v65
	v_fma_f32 v68, -v64, v67, v66
	v_fmac_f32_e32 v67, v68, v65
	v_fma_f32 v64, -v64, v67, v66
	v_div_fmas_f32 v64, v64, v65, v67
	v_div_fixup_f32 v61, v64, v61, 1.0
	v_div_scale_f32 v64, s[0:1], v60, v60, 1.0
	v_rcp_f32_e32 v65, v64
	v_pk_mul_f32 v[58:59], v[58:59], v[164:165]
	v_fma_f32 v66, -v64, v65, 1.0
	v_fmac_f32_e32 v65, v66, v65
	v_div_scale_f32 v66, vcc, 1.0, v60, 1.0
	v_mul_f32_e32 v67, v66, v65
	v_fma_f32 v68, -v64, v67, v66
	v_fmac_f32_e32 v67, v68, v65
	v_fma_f32 v64, -v64, v67, v66
	v_div_fmas_f32 v64, v64, v65, v67
	v_div_fixup_f32 v60, v64, v60, 1.0
	v_pk_mul_f32 v[56:57], v[60:61], v[56:57]
	v_add3_u32 v64, v179, v218, v213
	v_pk_mul_f32 v[56:57], v[56:57], v[162:163]
	ds_write_b128 v214, v[52:55] offset:32768
	ds_write_b128 v214, v[56:59] offset:50176
	ds_read_b128 v[60:63], v215
	ds_read_b128 v[56:59], v216
	ds_read_b128 v[52:55], v217
	ds_read_b64 v[66:67], v64
	s_waitcnt lgkmcnt(3)
	v_add_f32_e32 v48, v48, v60
	v_mul_f32_e32 v48, 0xbfb8aa3b, v48
	v_exp_f32_e32 v48, v48
	s_waitcnt lgkmcnt(2)
	v_add_f32_e32 v44, v44, v56
	v_mul_f32_e32 v44, 0xbfb8aa3b, v44
	v_exp_f32_e32 v56, v44
	v_add_f32_e32 v48, 1.0, v48
	v_div_scale_f32 v60, s[0:1], v48, v48, 1.0
	v_rcp_f32_e32 v68, v60
	v_add_f32_e32 v49, v49, v61
	v_mul_f32_e32 v49, 0xbfb8aa3b, v49
	v_exp_f32_e32 v49, v49
	v_fma_f32 v69, -v60, v68, 1.0
	v_fmac_f32_e32 v68, v69, v68
	v_div_scale_f32 v69, vcc, 1.0, v48, 1.0
	v_mul_f32_e32 v70, v69, v68
	v_fma_f32 v71, -v60, v70, v69
	v_fmac_f32_e32 v70, v71, v68
	v_fma_f32 v60, -v60, v70, v69
	v_div_fmas_f32 v60, v60, v68, v70
	v_div_fixup_f32 v48, v60, v48, 1.0
	v_mul_f32_e32 v44, 0xc1000000, v48
	s_waitcnt lgkmcnt(1)
	v_mul_f32_e32 v44, v52, v44
	v_mul_f32_e32 v44, 0x3fb8aa3b, v44
	v_exp_f32_e32 v44, v44
	v_add_f32_e32 v49, 1.0, v49
	v_add_f32_e32 v45, v45, v57
	v_mul_f32_e32 v45, 0xbfb8aa3b, v45
	v_fma_f32 v48, -v44, v44, 1.0
	v_max_f32_e32 v48, 0, v48
	v_cmp_gt_f32_e32 vcc, s10, v48
	v_mul_f32_e32 v52, 0x4f800000, v48
	v_exp_f32_e32 v57, v45
	v_cndmask_b32_e32 v48, v48, v52, vcc
	v_sqrt_f32_e32 v52, v48
	v_add_f32_e32 v50, v50, v62
	v_mul_f32_e32 v50, 0xbfb8aa3b, v50
	v_exp_f32_e32 v50, v50
	v_add_u32_e32 v60, -1, v52
	v_fma_f32 v68, -v60, v52, v48
	v_cmp_ge_f32_e64 s[0:1], 0, v68
	v_add_u32_e32 v68, 1, v52
	v_add_f32_e32 v50, 1.0, v50
	v_cndmask_b32_e64 v60, v52, v60, s[0:1]
	v_fma_f32 v52, -v68, v52, v48
	v_cmp_lt_f32_e64 s[0:1], 0, v52
	v_add_f32_e32 v46, v46, v58
	v_mul_f32_e32 v46, 0xbfb8aa3b, v46
	v_cndmask_b32_e64 v52, v60, v68, s[0:1]
	v_mul_f32_e32 v60, 0x37800000, v52
	v_cndmask_b32_e32 v52, v52, v60, vcc
	v_cmp_class_f32_e32 vcc, v48, v169
	v_add_f32_e32 v51, v51, v63
	v_mul_f32_e32 v51, 0xbfb8aa3b, v51
	v_cndmask_b32_e32 v48, v52, v48, vcc
	v_div_scale_f32 v52, s[0:1], v49, v49, 1.0
	v_rcp_f32_e32 v60, v52
	v_exp_f32_e32 v51, v51
	v_add_f32_e32 v47, v47, v59
	v_mul_f32_e32 v47, 0xbfb8aa3b, v47
	v_fma_f32 v61, -v52, v60, 1.0
	v_fmac_f32_e32 v60, v61, v60
	v_div_scale_f32 v61, vcc, 1.0, v49, 1.0
	v_mul_f32_e32 v68, v61, v60
	v_fma_f32 v69, -v52, v68, v61
	v_fmac_f32_e32 v68, v69, v60
	v_fma_f32 v52, -v52, v68, v61
	v_div_fmas_f32 v52, v52, v60, v68
	v_div_fixup_f32 v49, v52, v49, 1.0
	v_mul_f32_e32 v45, 0xc1000000, v49
	v_mul_f32_e32 v45, v53, v45
	v_mul_f32_e32 v45, 0x3fb8aa3b, v45
	v_exp_f32_e32 v45, v45
	v_add_f32_e32 v51, 1.0, v51
	s_waitcnt lgkmcnt(0)
	v_lshlrev_b32_e32 v64, 16, v66
	v_and_b32_e32 v65, 0xffff0000, v66
	v_fma_f32 v49, -v45, v45, 1.0
	v_max_f32_e32 v49, 0, v49
	v_cmp_gt_f32_e32 vcc, s10, v49
	v_mul_f32_e32 v52, 0x4f800000, v49
	v_lshlrev_b32_e32 v66, 16, v67
	v_cndmask_b32_e32 v49, v49, v52, vcc
	v_sqrt_f32_e32 v52, v49
	v_and_b32_e32 v67, 0xffff0000, v67
	v_add_u32_e32 v53, -1, v52
	v_fma_f32 v60, -v53, v52, v49
	v_cmp_ge_f32_e64 s[0:1], 0, v60
	v_add_u32_e32 v60, 1, v52
	s_nop 0
	v_cndmask_b32_e64 v53, v52, v53, s[0:1]
	v_fma_f32 v52, -v60, v52, v49
	v_cmp_lt_f32_e64 s[0:1], 0, v52
	s_nop 1
	v_cndmask_b32_e64 v52, v53, v60, s[0:1]
	v_mul_f32_e32 v53, 0x37800000, v52
	v_cndmask_b32_e32 v52, v52, v53, vcc
	v_cmp_class_f32_e32 vcc, v49, v169
	s_nop 1
	v_cndmask_b32_e32 v49, v52, v49, vcc
	v_div_scale_f32 v52, s[0:1], v50, v50, 1.0
	v_rcp_f32_e32 v53, v52
	s_nop 0
	v_fma_f32 v60, -v52, v53, 1.0
	v_fmac_f32_e32 v53, v60, v53
	v_div_scale_f32 v60, vcc, 1.0, v50, 1.0
	v_mul_f32_e32 v61, v60, v53
	v_fma_f32 v62, -v52, v61, v60
	v_fmac_f32_e32 v61, v62, v53
	v_fma_f32 v52, -v52, v61, v60
	v_div_fmas_f32 v52, v52, v53, v61
	v_div_fixup_f32 v50, v52, v50, 1.0
	v_exp_f32_e32 v52, v46
	v_mul_f32_e32 v46, 0xc1000000, v50
	v_mul_f32_e32 v46, v54, v46
	v_mul_f32_e32 v46, 0x3fb8aa3b, v46
	v_exp_f32_e32 v46, v46
	s_nop 0
	v_fma_f32 v50, -v46, v46, 1.0
	v_max_f32_e32 v50, 0, v50
	v_cmp_gt_f32_e32 vcc, s10, v50
	v_mul_f32_e32 v53, 0x4f800000, v50
	s_nop 0
	v_cndmask_b32_e32 v50, v50, v53, vcc
	v_sqrt_f32_e32 v53, v50
	s_nop 0
	v_add_u32_e32 v54, -1, v53
	v_fma_f32 v58, -v54, v53, v50
	v_cmp_ge_f32_e64 s[0:1], 0, v58
	v_add_u32_e32 v58, 1, v53
	s_nop 0
	v_cndmask_b32_e64 v54, v53, v54, s[0:1]
	v_fma_f32 v53, -v58, v53, v50
	v_cmp_lt_f32_e64 s[0:1], 0, v53
	s_nop 1
	v_cndmask_b32_e64 v53, v54, v58, s[0:1]
	v_mul_f32_e32 v54, 0x37800000, v53
	v_cndmask_b32_e32 v53, v53, v54, vcc
	v_cmp_class_f32_e32 vcc, v50, v169
	s_nop 1
	v_cndmask_b32_e32 v50, v53, v50, vcc
	v_div_scale_f32 v53, s[0:1], v51, v51, 1.0
	v_rcp_f32_e32 v54, v53
	s_nop 0
	v_fma_f32 v58, -v53, v54, 1.0
	v_fmac_f32_e32 v54, v58, v54
	v_div_scale_f32 v58, vcc, 1.0, v51, 1.0
	v_mul_f32_e32 v60, v58, v54
	v_fma_f32 v61, -v53, v60, v58
	v_fmac_f32_e32 v60, v61, v54
	v_fma_f32 v53, -v53, v60, v58
	v_div_fmas_f32 v53, v53, v54, v60
	v_div_fixup_f32 v51, v53, v51, 1.0
	v_exp_f32_e32 v53, v47
	v_mul_f32_e32 v47, 0xc1000000, v51
	v_mul_f32_e32 v47, v55, v47
	v_mul_f32_e32 v47, 0x3fb8aa3b, v47
	v_exp_f32_e32 v47, v47
	v_pk_add_f32 v[52:53], v[52:53], 1.0 op_sel_hi:[1,0]
	v_fma_f32 v51, -v47, v47, 1.0
	v_max_f32_e32 v51, 0, v51
	v_cmp_gt_f32_e32 vcc, s10, v51
	v_mul_f32_e32 v54, 0x4f800000, v51
	s_nop 0
	v_cndmask_b32_e32 v51, v51, v54, vcc
	v_sqrt_f32_e32 v54, v51
	s_nop 0
	v_add_u32_e32 v55, -1, v54
	v_fma_f32 v58, -v55, v54, v51
	v_cmp_ge_f32_e64 s[0:1], 0, v58
	v_add_u32_e32 v58, 1, v54
	s_nop 0
	v_cndmask_b32_e64 v55, v54, v55, s[0:1]
	v_fma_f32 v54, -v58, v54, v51
	v_cmp_lt_f32_e64 s[0:1], 0, v54
	s_nop 1
	v_cndmask_b32_e64 v54, v55, v58, s[0:1]
	v_mul_f32_e32 v55, 0x37800000, v54
	v_cndmask_b32_e32 v54, v54, v55, vcc
	v_cmp_class_f32_e32 vcc, v51, v169
	s_nop 1
	v_cndmask_b32_e32 v51, v54, v51, vcc
	v_pk_add_f32 v[54:55], v[56:57], 1.0 op_sel_hi:[1,0]
	v_div_scale_f32 v56, s[0:1], v53, v53, 1.0
	v_rcp_f32_e32 v57, v56
	s_nop 0
	v_fma_f32 v58, -v56, v57, 1.0
	v_fmac_f32_e32 v57, v58, v57
	v_div_scale_f32 v58, vcc, 1.0, v53, 1.0
	v_mul_f32_e32 v59, v58, v57
	v_fma_f32 v60, -v56, v59, v58
	v_fmac_f32_e32 v59, v60, v57
	v_fma_f32 v56, -v56, v59, v58
	v_div_fmas_f32 v56, v56, v57, v59
	v_div_fixup_f32 v53, v56, v53, 1.0
	v_div_scale_f32 v56, s[0:1], v52, v52, 1.0
	v_rcp_f32_e32 v57, v56
	s_nop 0
	v_fma_f32 v58, -v56, v57, 1.0
	v_fmac_f32_e32 v57, v58, v57
	v_div_scale_f32 v58, vcc, 1.0, v52, 1.0
	v_mul_f32_e32 v59, v58, v57
	v_fma_f32 v60, -v56, v59, v58
	v_fmac_f32_e32 v59, v60, v57
	v_fma_f32 v56, -v56, v59, v58
	v_div_fmas_f32 v56, v56, v57, v59
	v_div_fixup_f32 v52, v56, v52, 1.0
	v_div_scale_f32 v56, s[0:1], v55, v55, 1.0
	v_rcp_f32_e32 v57, v56
	v_pk_mul_f32 v[50:51], v[52:53], v[50:51]
	v_fma_f32 v58, -v56, v57, 1.0
	v_fmac_f32_e32 v57, v58, v57
	v_div_scale_f32 v58, vcc, 1.0, v55, 1.0
	v_mul_f32_e32 v59, v58, v57
	v_fma_f32 v60, -v56, v59, v58
	v_fmac_f32_e32 v59, v60, v57
	v_fma_f32 v56, -v56, v59, v58
	v_div_fmas_f32 v56, v56, v57, v59
	v_div_fixup_f32 v55, v56, v55, 1.0
	v_div_scale_f32 v56, s[0:1], v54, v54, 1.0
	v_rcp_f32_e32 v57, v56
	v_pk_mul_f32 v[50:51], v[50:51], v[66:67]
	v_fma_f32 v58, -v56, v57, 1.0
	v_fmac_f32_e32 v57, v58, v57
	v_div_scale_f32 v58, vcc, 1.0, v54, 1.0
	v_mul_f32_e32 v59, v58, v57
	v_fma_f32 v60, -v56, v59, v58
	v_fmac_f32_e32 v59, v60, v57
	v_fma_f32 v56, -v56, v59, v58
	v_div_fmas_f32 v56, v56, v57, v59
	v_div_fixup_f32 v54, v56, v54, 1.0
	v_pk_mul_f32 v[48:49], v[54:55], v[48:49]
	s_nop 0
	v_pk_mul_f32 v[48:49], v[48:49], v[64:65]
	ds_write_b128 v214, v[44:47] offset:32832
	ds_write_b128 v214, v[48:51] offset:50240
	s_waitcnt lgkmcnt(0)
	s_barrier
	s_and_saveexec_b64 s[0:1], s[38:39]
	s_cbranch_execz .LBB0_472
	s_setprio 3
	s_mov_b32 s28, 0
	s_and_b64 vcc, s[88:89], exec
	s_cbranch_scc0 .Lscan32_rinit
	v_mov_b32_e32 v60, v195
	ds_read_b32 v44, v60 offset:32768
	ds_read_b32 v45, v60 offset:50176
	ds_read_b32 v46, v60 offset:32912
	ds_read_b32 v47, v60 offset:50320
	ds_read_b32 v48, v60 offset:33056
	ds_read_b32 v49, v60 offset:50464
	ds_read_b32 v50, v60 offset:33200
	ds_read_b32 v51, v60 offset:50608
	ds_read_b32 v52, v60 offset:32768
	ds_read_b32 v53, v60 offset:32768
	ds_read_b32 v54, v60 offset:32768
	ds_read_b32 v55, v60 offset:32768

.Lscan32_done:
	s_setprio 0

.Llru16_noba:
	ds_read_b128 v[54:57], v101
	v_mfma_f32_16x16x32_bf16 v[58:61], v[58:61], v[62:65], v[44:47]
	s_nop 2
	v_add_u32_e32 v45, v104, v126
	v_mfma_f32_16x16x32_bf16 v[46:49], v[90:93], v[62:65], v[48:51]
	s_waitcnt lgkmcnt(0)
	s_nop 1
	v_add_f32_e32 v44, v58, v54
	v_mul_f32_e32 v44, 0xbfb8aa3b, v44
	v_exp_f32_e32 v44, v44
	ds_read_b64 v[92:93], v45
	ds_read_b128 v[50:53], v102
	ds_read_b128 v[62:65], v103
	v_add_f32_e32 v57, v61, v57
	v_add_f32_e32 v44, 1.0, v44
	v_div_scale_f32 v45, s[0:1], v44, v44, 1.0
	v_rcp_f32_e32 v54, v45
	s_waitcnt lgkmcnt(1)
	v_add_f32_e32 v46, v46, v50
	v_mul_f32_e32 v46, 0xbfb8aa3b, v46
	v_add_f32_e32 v47, v47, v51
	v_fma_f32 v58, -v45, v54, 1.0
	v_fmac_f32_e32 v54, v58, v54
	v_div_scale_f32 v58, vcc, 1.0, v44, 1.0
	v_mul_f32_e32 v91, v58, v54
	v_fma_f32 v126, -v45, v91, v58
	v_fmac_f32_e32 v91, v126, v54
	v_fma_f32 v45, -v45, v91, v58
	v_div_fmas_f32 v45, v45, v54, v91
	v_div_fixup_f32 v44, v45, v44, 1.0
	v_mul_f32_e32 v44, 0xc1000000, v44
	s_waitcnt lgkmcnt(0)
	v_mul_f32_e32 v44, v62, v44
	v_mul_f32_e32 v44, 0x3fb8aa3b, v44
	v_exp_f32_e32 v44, v44
	v_mul_f32_e32 v47, 0xbfb8aa3b, v47
	v_mul_f32_e32 v57, 0xbfb8aa3b, v57
	v_exp_f32_e32 v57, v57
	v_fma_f32 v45, -v44, v44, 1.0
	v_max_f32_e32 v45, 0, v45
	v_cmp_gt_f32_e64 s[0:1], s10, v45
	v_mul_f32_e32 v54, 0x4f800000, v45
	v_add_f32_e32 v57, 1.0, v57
	v_cndmask_b32_e64 v58, v45, v54, s[0:1]
	v_sqrt_f32_e32 v45, v58
	v_exp_f32_e32 v54, v46
	v_add_f32_e32 v48, v48, v52
	v_add_f32_e32 v49, v49, v53
	v_add_u32_e32 v46, -1, v45
	v_fma_f32 v50, -v46, v45, v58
	v_cmp_ge_f32_e32 vcc, 0, v50
	v_add_f32_e32 v50, v59, v55
	v_mul_f32_e32 v50, 0xbfb8aa3b, v50
	v_exp_f32_e32 v50, v50
	v_add_u32_e32 v55, 1, v45
	v_cndmask_b32_e32 v46, v45, v46, vcc
	v_fma_f32 v45, -v55, v45, v58
	v_add_f32_e32 v50, 1.0, v50
	v_div_scale_f32 v59, s[26:27], v50, v50, 1.0
	v_rcp_f32_e32 v62, v59
	v_cmp_lt_f32_e32 vcc, 0, v45
	v_mul_f32_e32 v48, 0xbfb8aa3b, v48
	v_mul_f32_e32 v49, 0xbfb8aa3b, v49
	v_fma_f32 v45, -v59, v62, 1.0
	v_cndmask_b32_e32 v46, v46, v55, vcc
	v_fmac_f32_e32 v62, v45, v62
	v_div_scale_f32 v45, vcc, 1.0, v50, 1.0
	v_mul_f32_e32 v126, v45, v62
	v_fma_f32 v127, -v59, v126, v45
	v_fmac_f32_e32 v126, v127, v62
	v_fma_f32 v45, -v59, v126, v45
	v_div_fmas_f32 v45, v45, v62, v126
	v_div_fixup_f32 v45, v45, v50, 1.0
	v_mul_f32_e32 v45, 0xc1000000, v45
	v_mul_f32_e32 v45, v63, v45
	v_mul_f32_e32 v45, 0x3fb8aa3b, v45
	v_exp_f32_e32 v45, v45
	v_mul_f32_e32 v55, 0x37800000, v46
	v_cndmask_b32_e64 v46, v46, v55, s[0:1]
	v_cmp_class_f32_e32 vcc, v58, v169
	v_exp_f32_e32 v48, v48
	v_exp_f32_e32 v49, v49
	v_cndmask_b32_e32 v50, v46, v58, vcc
	v_fma_f32 v46, -v45, v45, 1.0
	v_max_f32_e32 v46, 0, v46
	v_cmp_gt_f32_e64 s[0:1], s10, v46
	v_mul_f32_e32 v55, 0x4f800000, v46
	v_pk_add_f32 v[48:49], v[48:49], 1.0 op_sel_hi:[1,0]
	v_cndmask_b32_e64 v58, v46, v55, s[0:1]
	v_sqrt_f32_e32 v46, v58
	v_exp_f32_e32 v55, v47
	v_lshlrev_b32_e32 v90, 16, v92
	v_and_b32_e32 v91, 0xffff0000, v92
	v_add_u32_e32 v47, -1, v46
	v_fma_f32 v51, -v47, v46, v58
	v_cmp_ge_f32_e32 vcc, 0, v51
	v_add_f32_e32 v51, v60, v56
	v_mul_f32_e32 v51, 0xbfb8aa3b, v51
	v_exp_f32_e32 v51, v51
	v_add_u32_e32 v56, 1, v46
	v_cndmask_b32_e32 v47, v46, v47, vcc
	v_fma_f32 v46, -v56, v46, v58
	v_add_f32_e32 v51, 1.0, v51
	v_div_scale_f32 v59, s[26:27], v51, v51, 1.0
	v_rcp_f32_e32 v60, v59
	v_cmp_lt_f32_e32 vcc, 0, v46
	v_pk_add_f32 v[54:55], v[54:55], 1.0 op_sel_hi:[1,0]
	v_lshlrev_b32_e32 v92, 16, v93
	v_fma_f32 v46, -v59, v60, 1.0
	v_cndmask_b32_e32 v47, v47, v56, vcc
	v_fmac_f32_e32 v60, v46, v60
	v_div_scale_f32 v46, vcc, 1.0, v51, 1.0
	v_mul_f32_e32 v62, v46, v60
	v_fma_f32 v63, -v59, v62, v46
	v_fmac_f32_e32 v62, v63, v60
	v_fma_f32 v46, -v59, v62, v46
	v_div_fmas_f32 v46, v46, v60, v62
	v_div_fixup_f32 v46, v46, v51, 1.0
	v_mul_f32_e32 v46, 0xc1000000, v46
	v_mul_f32_e32 v46, v64, v46
	v_mul_f32_e32 v46, 0x3fb8aa3b, v46
	v_exp_f32_e32 v46, v46
	v_mul_f32_e32 v56, 0x37800000, v47
	v_cndmask_b32_e64 v47, v47, v56, s[0:1]
	v_cmp_class_f32_e32 vcc, v58, v169
	v_div_scale_f32 v59, s[26:27], v57, v57, 1.0
	s_nop 0
	v_cndmask_b32_e32 v51, v47, v58, vcc
	v_fma_f32 v47, -v46, v46, 1.0
	v_max_f32_e32 v47, 0, v47
	v_cmp_gt_f32_e64 s[0:1], s10, v47
	v_mul_f32_e32 v56, 0x4f800000, v47
	v_rcp_f32_e32 v60, v59
	v_cndmask_b32_e64 v56, v47, v56, s[0:1]
	v_sqrt_f32_e32 v47, v56
	v_and_b32_e32 v93, 0xffff0000, v93
	v_add_u32_e32 v52, -1, v47
	v_fma_f32 v58, -v52, v47, v56
	v_cmp_ge_f32_e32 vcc, 0, v58
	v_add_u32_e32 v58, 1, v47
	s_nop 0
	v_cndmask_b32_e32 v52, v47, v52, vcc
	v_fma_f32 v47, -v58, v47, v56
	v_cmp_lt_f32_e32 vcc, 0, v47
	v_fma_f32 v47, -v59, v60, 1.0
	v_fmac_f32_e32 v60, v47, v60
	v_cndmask_b32_e32 v52, v52, v58, vcc
	v_div_scale_f32 v47, vcc, 1.0, v57, 1.0
	v_mul_f32_e32 v61, v47, v60
	v_fma_f32 v62, -v59, v61, v47
	v_fmac_f32_e32 v61, v62, v60
	v_fma_f32 v47, -v59, v61, v47
	v_div_fmas_f32 v47, v47, v60, v61
	v_div_fixup_f32 v47, v47, v57, 1.0
	v_mul_f32_e32 v47, 0xc1000000, v47
	v_mul_f32_e32 v47, v65, v47
	v_mul_f32_e32 v47, 0x3fb8aa3b, v47
	v_exp_f32_e32 v47, v47
	v_mul_f32_e32 v58, 0x37800000, v52
	v_cndmask_b32_e64 v52, v52, v58, s[0:1]
	v_cmp_class_f32_e32 vcc, v56, v169
	s_nop 1
	v_cndmask_b32_e32 v52, v52, v56, vcc
	v_fma_f32 v56, -v47, v47, 1.0
	v_max_f32_e32 v56, 0, v56
	v_cmp_gt_f32_e32 vcc, s10, v56
	v_mul_f32_e32 v57, 0x4f800000, v56
	s_nop 0
	v_cndmask_b32_e32 v56, v56, v57, vcc
	v_sqrt_f32_e32 v57, v56
	s_nop 0
	v_add_u32_e32 v53, -1, v57
	v_fma_f32 v58, -v53, v57, v56
	v_cmp_ge_f32_e64 s[0:1], 0, v58
	v_add_u32_e32 v58, 1, v57
	s_nop 0
	v_cndmask_b32_e64 v53, v57, v53, s[0:1]
	v_fma_f32 v57, -v58, v57, v56
	v_cmp_lt_f32_e64 s[0:1], 0, v57
	s_nop 1
	v_cndmask_b32_e64 v53, v53, v58, s[0:1]
	v_mul_f32_e32 v57, 0x37800000, v53
	v_cndmask_b32_e32 v53, v53, v57, vcc
	v_div_scale_f32 v57, s[0:1], v49, v49, 1.0
	v_rcp_f32_e32 v58, v57
	v_cmp_class_f32_e32 vcc, v56, v169
	s_nop 1
	v_cndmask_b32_e32 v53, v53, v56, vcc
	v_fma_f32 v56, -v57, v58, 1.0
	v_fmac_f32_e32 v58, v56, v58
	v_div_scale_f32 v56, vcc, 1.0, v49, 1.0
	v_mul_f32_e32 v59, v56, v58
	v_fma_f32 v60, -v57, v59, v56
	v_fmac_f32_e32 v59, v60, v58
	v_fma_f32 v56, -v57, v59, v56
	v_div_scale_f32 v57, s[0:1], v48, v48, 1.0
	v_rcp_f32_e32 v60, v57
	v_div_fmas_f32 v56, v56, v58, v59
	v_div_fixup_f32 v49, v56, v49, 1.0
	v_fma_f32 v56, -v57, v60, 1.0
	v_fmac_f32_e32 v60, v56, v60
	v_div_scale_f32 v56, vcc, 1.0, v48, 1.0
	v_mul_f32_e32 v58, v56, v60
	v_fma_f32 v59, -v57, v58, v56
	v_fmac_f32_e32 v58, v59, v60
	v_fma_f32 v56, -v57, v58, v56
	v_div_scale_f32 v57, s[0:1], v55, v55, 1.0
	v_rcp_f32_e32 v59, v57
	v_div_fmas_f32 v56, v56, v60, v58
	v_div_fixup_f32 v48, v56, v48, 1.0
	v_pk_mul_f32 v[48:49], v[48:49], v[52:53]
	v_fma_f32 v56, -v57, v59, 1.0
	v_fmac_f32_e32 v59, v56, v59
	v_div_scale_f32 v56, vcc, 1.0, v55, 1.0
	v_mul_f32_e32 v58, v56, v59
	v_fma_f32 v60, -v57, v58, v56
	v_fmac_f32_e32 v58, v60, v59
	v_fma_f32 v56, -v57, v58, v56
	v_div_scale_f32 v57, s[0:1], v54, v54, 1.0
	v_rcp_f32_e32 v60, v57
	v_div_fmas_f32 v56, v56, v59, v58
	v_div_fixup_f32 v55, v56, v55, 1.0
	v_fma_f32 v56, -v57, v60, 1.0
	v_fmac_f32_e32 v60, v56, v60
	v_div_scale_f32 v56, vcc, 1.0, v54, 1.0
	v_mul_f32_e32 v58, v56, v60
	v_fma_f32 v59, -v57, v58, v56
	v_fmac_f32_e32 v58, v59, v60
	v_fma_f32 v56, -v57, v58, v56
	v_div_fmas_f32 v56, v56, v60, v58
	v_div_fixup_f32 v54, v56, v54, 1.0
	v_pk_mul_f32 v[54:55], v[54:55], v[50:51]
	v_pk_mul_f32 v[50:51], v[48:49], v[92:93]
	v_pk_mul_f32 v[48:49], v[54:55], v[90:91]
	ds_write_b128 v105, v[44:47] offset:32768
	ds_write_b128 v105, v[48:51] offset:50176
	s_waitcnt lgkmcnt(0)
	s_barrier
	s_and_saveexec_b64 s[0:1], s[36:37]
	s_cbranch_execz .LBB0_540
	s_setprio 3
	s_mov_b32 s26, 0
	s_and_b64 s[28:29], s[38:39], exec
	s_cbranch_scc0 .Lscan16_rinit
	v_mov_b32_e32 v44, v74
	ds_read_b32 v46, v44 offset:32768
	ds_read_b32 v47, v44 offset:50176
	ds_read_b32 v50, v44 offset:32848
	ds_read_b32 v51, v44 offset:50256
	ds_read_b32 v54, v44 offset:32928
	ds_read_b32 v55, v44 offset:50336
	ds_read_b32 v58, v44 offset:33008
	ds_read_b32 v59, v44 offset:50416
	ds_read_b32 v62, v44 offset:32768
	ds_read_b32 v63, v44 offset:32768
	ds_read_b32 v90, v44 offset:32768
	ds_read_b32 v91, v44 offset:32768

.Lscan16_done:
	s_setprio 0
	s_branch .LBB0_540
